# all GEMM accumulator clears (small, in-proj first+per-tile, group, out-proj) use 64-bit moves
# speedup vs baseline: 1.0075x; 1.0009x over previous
.LBB0_126:
	s_xor_b64 s[74:75], s[8:9], -1
	s_and_b64 s[8:9], s[8:9], exec
	s_cselect_b32 s8, s43, s39
	s_cselect_b32 s9, s42, s38
	s_cselect_b32 s35, s63, s83
	s_cselect_b32 s36, s62, s82
	s_add_u32 s38, s38, 0x40080
	s_addc_u32 s39, s39, 0
	s_add_u32 s37, s82, 0x100
	v_mov_b32_e32 v0, 0
	s_addc_u32 s41, s83, 0
	s_mov_b32 s72, -2
	v_mov_b32_e32 v1, v0
	v_mov_b64_e32 v[2:3], v[0:1]
	v_mov_b64_e32 v[4:5], v[0:1]
	v_mov_b64_e32 v[6:7], v[0:1]
	v_mov_b64_e32 v[16:17], v[0:1]
	v_mov_b64_e32 v[18:19], v[0:1]
	v_mov_b64_e32 v[20:21], v[0:1]
	v_mov_b64_e32 v[22:23], v[0:1]
	v_mov_b64_e32 v[32:33], v[0:1]
	v_mov_b64_e32 v[34:35], v[0:1]
	v_mov_b64_e32 v[36:37], v[0:1]
	v_mov_b64_e32 v[38:39], v[0:1]
	v_mov_b64_e32 v[48:49], v[0:1]
	v_mov_b64_e32 v[50:51], v[0:1]
	v_mov_b64_e32 v[52:53], v[0:1]
	v_mov_b64_e32 v[54:55], v[0:1]
	v_mov_b64_e32 v[8:9], v[0:1]
	v_mov_b64_e32 v[10:11], v[0:1]
	v_mov_b64_e32 v[12:13], v[0:1]
	v_mov_b64_e32 v[14:15], v[0:1]
	v_mov_b64_e32 v[24:25], v[0:1]
	v_mov_b64_e32 v[26:27], v[0:1]
	v_mov_b64_e32 v[28:29], v[0:1]
	v_mov_b64_e32 v[30:31], v[0:1]
	v_mov_b64_e32 v[40:41], v[0:1]
	v_mov_b64_e32 v[42:43], v[0:1]
	v_mov_b64_e32 v[44:45], v[0:1]
	v_mov_b64_e32 v[46:47], v[0:1]
	v_mov_b64_e32 v[56:57], v[0:1]
	v_mov_b64_e32 v[58:59], v[0:1]
	v_mov_b64_e32 v[60:61], v[0:1]
	v_mov_b64_e32 v[62:63], v[0:1]
	v_mov_b64_e32 v[64:65], v[0:1]
	v_mov_b64_e32 v[66:67], v[0:1]
	v_mov_b64_e32 v[68:69], v[0:1]
	v_mov_b64_e32 v[70:71], v[0:1]
	v_mov_b64_e32 v[80:81], v[0:1]
	v_mov_b64_e32 v[82:83], v[0:1]
	v_mov_b64_e32 v[84:85], v[0:1]
	v_mov_b64_e32 v[86:87], v[0:1]
	v_mov_b64_e32 v[96:97], v[0:1]
	v_mov_b64_e32 v[98:99], v[0:1]
	v_mov_b64_e32 v[100:101], v[0:1]
	v_mov_b64_e32 v[102:103], v[0:1]
	v_mov_b64_e32 v[112:113], v[0:1]
	v_mov_b64_e32 v[114:115], v[0:1]
	v_mov_b64_e32 v[116:117], v[0:1]
	v_mov_b64_e32 v[118:119], v[0:1]
	v_mov_b64_e32 v[72:73], v[0:1]
	v_mov_b64_e32 v[74:75], v[0:1]
	v_mov_b64_e32 v[76:77], v[0:1]
	v_mov_b64_e32 v[78:79], v[0:1]
	v_mov_b64_e32 v[88:89], v[0:1]
	v_mov_b64_e32 v[90:91], v[0:1]
	v_mov_b64_e32 v[92:93], v[0:1]
	v_mov_b64_e32 v[94:95], v[0:1]
	v_mov_b64_e32 v[104:105], v[0:1]
	v_mov_b64_e32 v[106:107], v[0:1]
	v_mov_b64_e32 v[108:109], v[0:1]
	v_mov_b64_e32 v[110:111], v[0:1]
	v_mov_b64_e32 v[120:121], v[0:1]
	v_mov_b64_e32 v[122:123], v[0:1]
	v_mov_b64_e32 v[124:125], v[0:1]
	v_mov_b64_e32 v[126:127], v[0:1]

.LBB0_341:
	s_mul_i32 s7, s17, 0x11000
	v_readlane_b32 s8, v254, 8
	s_mul_hi_u32 s6, s17, 0x11000
	s_add_u32 s60, s8, s7
	v_readlane_b32 s7, v254, 9
	s_addc_u32 s61, s7, s6
	s_mul_i32 s7, s17, 0x352000
	v_readlane_b32 s8, v252, 35
	s_mul_hi_u32 s6, s17, 0x352000
	v_readlane_b32 s9, v252, 36
	s_add_u32 s80, s8, s7
	v_bfe_u32 v244, v9, 4, 2
	s_addc_u32 s81, s9, s6
	s_add_i32 s6, s21, 0xffffffa0
	v_and_b32_e32 v207, 15, v9
	v_lshlrev_b32_e32 v10, 4, v244
	v_lshlrev_b32_e32 v9, 2, v9
	v_writelane_b32 v252, s6, 47
	s_lshl_b32 s6, s0, 6
	v_lshl_or_b32 v10, v207, 6, v10
	s_lshl_b32 s0, s0, 13
	v_and_b32_e32 v9, 32, v9
	v_bitop3_b32 v11, v10, s0, v9 bitop3:0xde
	s_lshl_b32 s0, s1, 5
	s_and_b32 s30, s0, 0x60
	s_add_i32 m0, s91, 0x18000
	v_lshl_add_u64 v[6:7], v[6:7], 0, s[66:67]
	s_or_b32 s28, s21, 32
	s_lshl_b32 s0, s30, 7
	s_waitcnt vmcnt(4)
	s_barrier
	global_load_lds_dwordx4 v[6:7], off
	v_lshl_add_u64 v[4:5], v[4:5], 0, s[66:67]
	s_add_i32 m0, s91, 0x1a000
	s_add_i32 s31, s91, 0x8000
	s_add_i32 s34, s91, 0xa000
	v_bitop3_b32 v245, v10, s0, v9 bitop3:0xde
	global_load_lds_dwordx4 v[4:5], off
	v_lshl_add_u64 v[2:3], v[2:3], 0, s[66:67]
	s_mov_b32 m0, s31
	s_add_u32 s0, s58, 0x40080
	global_load_lds_dwordx4 v[2:3], off
	v_lshl_add_u64 v[0:1], v[0:1], 0, s[66:67]
	s_mov_b32 m0, s34
	s_addc_u32 s1, s59, 0
	global_load_lds_dwordx4 v[0:1], off
	s_add_i32 m0, s91, 0x1c000
	v_lshl_add_u64 v[0:1], s[0:1], 0, v[212:213]
	global_load_lds_dwordx4 v[0:1], off
	v_lshl_add_u64 v[0:1], s[0:1], 0, v[216:217]
	s_add_i32 m0, s91, 0x1e000
	v_cvt_f32_ubyte0_e32 v2, s27
	global_load_lds_dwordx4 v[0:1], off
	v_rcp_iflag_f32_e32 v2, v2
	s_sub_i32 s0, 0, s27
	v_writelane_b32 v255, s27, 27
	s_waitcnt vmcnt(6)
	v_mul_f32_e32 v0, 0x4f7ffffe, v2
	v_cvt_u32_f32_e32 v0, v0
	v_writelane_b32 v252, s6, 49
	s_mov_b32 s35, 0
	v_add_u32_e32 v246, 0, v11
	v_readfirstlane_b32 s1, v0
	v_mul_f32_e32 v0, 0x4f7ffffe, v8
	v_cvt_u32_f32_e32 v0, v0
	s_mul_i32 s0, s0, s1
	s_mul_hi_u32 s0, s1, s0
	s_add_i32 s0, s1, s0
	v_writelane_b32 v255, s0, 28
	s_sub_i32 s0, 0, s22
	v_readfirstlane_b32 s1, v0
	s_mul_i32 s0, s0, s1
	s_mul_hi_u32 s0, s1, s0
	s_add_i32 s0, s1, s0
	v_mov_b32_e32 v0, 0
	v_writelane_b32 v255, s0, 29
	v_mov_b32_e32 v1, v0
	v_mov_b64_e32 v[2:3], v[0:1]
	v_mov_b64_e32 v[4:5], v[0:1]
	v_mov_b64_e32 v[6:7], v[0:1]
	v_mov_b64_e32 v[8:9], v[0:1]
	v_mov_b64_e32 v[10:11], v[0:1]
	v_mov_b64_e32 v[12:13], v[0:1]
	v_mov_b64_e32 v[14:15], v[0:1]
	v_mov_b64_e32 v[16:17], v[0:1]
	v_mov_b64_e32 v[18:19], v[0:1]
	v_mov_b64_e32 v[20:21], v[0:1]
	v_mov_b64_e32 v[22:23], v[0:1]
	v_mov_b64_e32 v[24:25], v[0:1]
	v_mov_b64_e32 v[26:27], v[0:1]
	v_mov_b64_e32 v[28:29], v[0:1]
	v_mov_b64_e32 v[30:31], v[0:1]
	v_mov_b64_e32 v[32:33], v[0:1]
	v_mov_b64_e32 v[34:35], v[0:1]
	v_mov_b64_e32 v[36:37], v[0:1]
	v_mov_b64_e32 v[38:39], v[0:1]
	v_mov_b64_e32 v[40:41], v[0:1]
	v_mov_b64_e32 v[42:43], v[0:1]
	v_mov_b64_e32 v[44:45], v[0:1]
	v_mov_b64_e32 v[46:47], v[0:1]
	v_mov_b64_e32 v[50:51], v[0:1]
	v_mov_b64_e32 v[52:53], v[0:1]
	v_mov_b64_e32 v[54:55], v[0:1]
	v_mov_b64_e32 v[56:57], v[0:1]
	v_mov_b64_e32 v[58:59], v[0:1]
	v_mov_b64_e32 v[60:61], v[0:1]
	v_mov_b64_e32 v[62:63], v[0:1]
	v_mov_b64_e32 v[64:65], v[0:1]
	v_mov_b64_e32 v[66:67], v[0:1]
	v_mov_b64_e32 v[68:69], v[0:1]
	v_mov_b64_e32 v[70:71], v[0:1]
	v_mov_b64_e32 v[72:73], v[0:1]
	v_mov_b64_e32 v[74:75], v[0:1]
	v_mov_b64_e32 v[76:77], v[0:1]
	v_mov_b64_e32 v[78:79], v[0:1]
	v_mov_b64_e32 v[80:81], v[0:1]
	v_mov_b64_e32 v[82:83], v[0:1]
	v_mov_b64_e32 v[84:85], v[0:1]
	v_mov_b64_e32 v[86:87], v[0:1]
	v_mov_b64_e32 v[88:89], v[0:1]
	v_mov_b64_e32 v[90:91], v[0:1]
	v_mov_b64_e32 v[92:93], v[0:1]
	v_mov_b64_e32 v[94:95], v[0:1]
	v_mov_b64_e32 v[96:97], v[0:1]
	v_mov_b64_e32 v[98:99], v[0:1]
	v_mov_b64_e32 v[100:101], v[0:1]
	v_mov_b64_e32 v[102:103], v[0:1]
	v_mov_b64_e32 v[104:105], v[0:1]
	v_mov_b64_e32 v[106:107], v[0:1]
	v_mov_b64_e32 v[108:109], v[0:1]
	v_mov_b64_e32 v[110:111], v[0:1]
	v_mov_b64_e32 v[112:113], v[0:1]
	v_mov_b64_e32 v[114:115], v[0:1]
	v_mov_b64_e32 v[116:117], v[0:1]
	v_mov_b64_e32 v[118:119], v[0:1]
	v_mov_b64_e32 v[120:121], v[0:1]
	v_mov_b64_e32 v[122:123], v[0:1]
	v_mov_b64_e32 v[124:125], v[0:1]
	v_mov_b64_e32 v[126:127], v[0:1]
	v_mov_b64_e32 v[128:129], v[0:1]
	s_barrier
	s_branch .LBB0_343

.LBB0_909:
	s_add_u32 s54, s54, 0x80080
	s_addc_u32 s55, s55, 0
	s_add_u32 s8, s56, 0x100
	v_mov_b32_e32 v0, 0
	s_addc_u32 s9, s57, 0
	s_mov_b32 s36, -2
	v_mov_b32_e32 v1, v0
	v_mov_b64_e32 v[2:3], v[0:1]
	v_mov_b64_e32 v[4:5], v[0:1]
	v_mov_b64_e32 v[6:7], v[0:1]
	v_mov_b64_e32 v[16:17], v[0:1]
	v_mov_b64_e32 v[18:19], v[0:1]
	v_mov_b64_e32 v[20:21], v[0:1]
	v_mov_b64_e32 v[22:23], v[0:1]
	v_mov_b64_e32 v[32:33], v[0:1]
	v_mov_b64_e32 v[34:35], v[0:1]
	v_mov_b64_e32 v[36:37], v[0:1]
	v_mov_b64_e32 v[38:39], v[0:1]
	v_mov_b64_e32 v[58:59], v[0:1]
	v_mov_b64_e32 v[60:61], v[0:1]
	v_mov_b64_e32 v[62:63], v[0:1]
	v_mov_b64_e32 v[64:65], v[0:1]
	v_mov_b64_e32 v[8:9], v[0:1]
	v_mov_b64_e32 v[10:11], v[0:1]
	v_mov_b64_e32 v[12:13], v[0:1]
	v_mov_b64_e32 v[14:15], v[0:1]
	v_mov_b64_e32 v[24:25], v[0:1]
	v_mov_b64_e32 v[26:27], v[0:1]
	v_mov_b64_e32 v[28:29], v[0:1]
	v_mov_b64_e32 v[30:31], v[0:1]
	v_mov_b64_e32 v[40:41], v[0:1]
	v_mov_b64_e32 v[42:43], v[0:1]
	v_mov_b64_e32 v[44:45], v[0:1]
	v_mov_b64_e32 v[46:47], v[0:1]
	v_mov_b64_e32 v[74:75], v[0:1]
	v_mov_b64_e32 v[76:77], v[0:1]
	v_mov_b64_e32 v[78:79], v[0:1]
	v_mov_b64_e32 v[80:81], v[0:1]
	v_mov_b64_e32 v[82:83], v[0:1]
	v_mov_b64_e32 v[84:85], v[0:1]
	v_mov_b64_e32 v[86:87], v[0:1]
	v_mov_b64_e32 v[88:89], v[0:1]
	v_mov_b64_e32 v[98:99], v[0:1]
	v_mov_b64_e32 v[100:101], v[0:1]
	v_mov_b64_e32 v[102:103], v[0:1]
	v_mov_b64_e32 v[104:105], v[0:1]
	v_mov_b64_e32 v[114:115], v[0:1]
	v_mov_b64_e32 v[116:117], v[0:1]
	v_mov_b64_e32 v[118:119], v[0:1]
	v_mov_b64_e32 v[120:121], v[0:1]
	v_mov_b64_e32 v[130:131], v[0:1]
	v_mov_b64_e32 v[132:133], v[0:1]
	v_mov_b64_e32 v[134:135], v[0:1]
	v_mov_b64_e32 v[136:137], v[0:1]
	v_mov_b64_e32 v[90:91], v[0:1]
	v_mov_b64_e32 v[92:93], v[0:1]
	v_mov_b64_e32 v[94:95], v[0:1]
	v_mov_b64_e32 v[96:97], v[0:1]
	v_mov_b64_e32 v[106:107], v[0:1]
	v_mov_b64_e32 v[108:109], v[0:1]
	v_mov_b64_e32 v[110:111], v[0:1]
	v_mov_b64_e32 v[112:113], v[0:1]
	v_mov_b64_e32 v[122:123], v[0:1]
	v_mov_b64_e32 v[124:125], v[0:1]
	v_mov_b64_e32 v[126:127], v[0:1]
	v_mov_b64_e32 v[128:129], v[0:1]
	v_mov_b64_e32 v[142:143], v[0:1]
	v_mov_b64_e32 v[144:145], v[0:1]
	v_mov_b64_e32 v[146:147], v[0:1]
	v_mov_b64_e32 v[148:149], v[0:1]

.LBB0_995:
	s_xor_b64 s[62:63], s[8:9], -1
	s_and_b64 s[8:9], s[8:9], exec
	s_cselect_b32 s8, s59, s7
	s_cselect_b32 s9, s58, s6
	s_cselect_b32 s10, s61, s41
	s_cselect_b32 s11, s60, s40
	s_add_u32 s6, s6, 0x80080
	s_addc_u32 s7, s7, 0
	s_add_u32 s55, s40, 0x100
	v_mov_b32_e32 v0, 0
	s_addc_u32 s57, s41, 0
	s_mov_b32 s40, 0
	s_waitcnt lgkmcnt(0)
	v_mov_b32_e32 v1, v0
	v_mov_b64_e32 v[2:3], v[0:1]
	v_mov_b64_e32 v[4:5], v[0:1]
	v_mov_b64_e32 v[6:7], v[0:1]
	v_mov_b64_e32 v[16:17], v[0:1]
	v_mov_b64_e32 v[18:19], v[0:1]
	v_mov_b64_e32 v[20:21], v[0:1]
	v_mov_b64_e32 v[22:23], v[0:1]
	v_mov_b64_e32 v[32:33], v[0:1]
	v_mov_b64_e32 v[34:35], v[0:1]
	v_mov_b64_e32 v[36:37], v[0:1]
	v_mov_b64_e32 v[38:39], v[0:1]
	v_mov_b64_e32 v[50:51], v[0:1]
	v_mov_b64_e32 v[52:53], v[0:1]
	v_mov_b64_e32 v[54:55], v[0:1]
	v_mov_b64_e32 v[56:57], v[0:1]
	v_mov_b64_e32 v[8:9], v[0:1]
	v_mov_b64_e32 v[10:11], v[0:1]
	v_mov_b64_e32 v[12:13], v[0:1]
	v_mov_b64_e32 v[14:15], v[0:1]
	v_mov_b64_e32 v[24:25], v[0:1]
	v_mov_b64_e32 v[26:27], v[0:1]
	v_mov_b64_e32 v[28:29], v[0:1]
	v_mov_b64_e32 v[30:31], v[0:1]
	v_mov_b64_e32 v[40:41], v[0:1]
	v_mov_b64_e32 v[42:43], v[0:1]
	v_mov_b64_e32 v[44:45], v[0:1]
	v_mov_b64_e32 v[46:47], v[0:1]
	v_mov_b64_e32 v[58:59], v[0:1]
	v_mov_b64_e32 v[60:61], v[0:1]
	v_mov_b64_e32 v[62:63], v[0:1]
	v_mov_b64_e32 v[64:65], v[0:1]
	v_mov_b64_e32 v[66:67], v[0:1]
	v_mov_b64_e32 v[68:69], v[0:1]
	v_mov_b64_e32 v[70:71], v[0:1]
	v_mov_b64_e32 v[72:73], v[0:1]
	v_mov_b64_e32 v[82:83], v[0:1]
	v_mov_b64_e32 v[84:85], v[0:1]
	v_mov_b64_e32 v[86:87], v[0:1]
	v_mov_b64_e32 v[88:89], v[0:1]
	v_mov_b64_e32 v[98:99], v[0:1]
	v_mov_b64_e32 v[100:101], v[0:1]
	v_mov_b64_e32 v[102:103], v[0:1]
	v_mov_b64_e32 v[104:105], v[0:1]
	v_mov_b64_e32 v[114:115], v[0:1]
	v_mov_b64_e32 v[116:117], v[0:1]
	v_mov_b64_e32 v[118:119], v[0:1]
	v_mov_b64_e32 v[120:121], v[0:1]
	v_mov_b64_e32 v[74:75], v[0:1]
	v_mov_b64_e32 v[76:77], v[0:1]
	v_mov_b64_e32 v[78:79], v[0:1]
	v_mov_b64_e32 v[80:81], v[0:1]
	v_mov_b64_e32 v[90:91], v[0:1]
	v_mov_b64_e32 v[92:93], v[0:1]
	v_mov_b64_e32 v[94:95], v[0:1]
	v_mov_b64_e32 v[96:97], v[0:1]
	v_mov_b64_e32 v[106:107], v[0:1]
	v_mov_b64_e32 v[108:109], v[0:1]
	v_mov_b64_e32 v[110:111], v[0:1]
	v_mov_b64_e32 v[112:113], v[0:1]
	v_mov_b64_e32 v[122:123], v[0:1]
	v_mov_b64_e32 v[124:125], v[0:1]
	v_mov_b64_e32 v[126:127], v[0:1]
	v_mov_b64_e32 v[128:129], v[0:1]
